# P1 in-proj epilogue: 8 rs loads issued together, per-row-group vmcnt(0) drains removed (kept on rotary path); plus P5 epilogue preload
# speedup vs baseline: 1.0098x; 1.0098x over previous
;     __device__ __forceinline__ void operator()(const f32x4 (&acc)[2][2][4][2], const Unit& u, int wr, int wc, int fr, int fq) const {
;     ...
;         const int row0 = u.pm * BM + wr * 64 + fr, col0 = cb + wc * 32 + 8 * fq;
; #pragma unroll
;         for (int ai = 0; ai < 2; ++ai)
; #pragma unroll
;             for (int m = 0; m < 4; ++m) {
;                 const int row = row0 + ai * HALF + m * 16; const float rsv = rs[row] * sc;
;                 f32x4 cs = (f32x4){1.f, 1.f, 1.f, 1.f}, sn = (f32x4){0.f, 0.f, 0.f, 0.f};
;                 if (ropel) { const int t = row & 8191; cs = *(const f32x4*)(rope + t * 8 + 4 * fq); sn = *(const f32x4*)(rope + 65536 + t * 8 + 4 * fq); }
;                 bf16_t* rowp = base + (size_t)row * ldc + col0;
.LBB0_247:
	v_lshl_add_u32 v158, s2, 8, v168
	v_ashrrev_i32_e32 v159, 31, v158
	v_lshl_add_u64 v[160:161], v[158:159], 2, s[6:7]
	global_load_dword v162, v[160:161], off
	global_load_dword v231, v[160:161], off offset:64
	global_load_dword v232, v[160:161], off offset:128
	global_load_dword v233, v[160:161], off offset:192
	global_load_dword v234, v[160:161], off offset:512
	global_load_dword v235, v[160:161], off offset:576
	global_load_dword v236, v[160:161], off offset:640
	global_load_dword v237, v[160:161], off offset:704
	s_and_b64 s[88:89], s[78:79], s[94:95]
	v_mov_b32_e32 v132, 0
	v_mov_b32_e32 v128, 1.0
	v_mov_b32_e32 v129, 1.0
	v_mov_b32_e32 v130, 1.0
	v_mov_b32_e32 v131, 1.0
	v_mov_b32_e32 v133, 0
	v_mov_b32_e32 v134, 0
	v_mov_b32_e32 v135, 0
	s_and_saveexec_b64 s[2:3], s[88:89]
	s_cbranch_execz .LBB0_249
	v_lshlrev_b32_e32 v128, 5, v158
	v_and_b32_e32 v144, 0x3f9e0, v128
	v_lshl_add_u64 v[132:133], v[148:149], 0, v[144:145]
	v_lshl_add_u64 v[128:129], v[146:147], 0, v[144:145]
	global_load_dwordx4 v[128:131], v[128:129], off
	s_nop 0
	global_load_dwordx4 v[132:135], v[132:133], off

; __device__ __forceinline__ unsigned cvt_pk_bf16(float lo, float hi) { unsigned r; asm volatile("v_cvt_pk_bf16_f32 %0, %1, %2" : "=v"(r) : "v"(lo), "v"(hi)); return r; }
;     __device__ __forceinline__ void operator()(const f32x4 (&acc)[2][2][4][2], const Unit& u, int wr, int wc, int fr, int fq) const {
;     ...
;                 const int row = row0 + ai * HALF + m * 16; const float rsv = rs[row] * sc;
;                 f32x4 cs = (f32x4){1.f, 1.f, 1.f, 1.f}, sn = (f32x4){0.f, 0.f, 0.f, 0.f};
;                 if (ropel) { const int t = row & 8191; cs = *(const f32x4*)(rope + t * 8 + 4 * fq); sn = *(const f32x4*)(rope + 65536 + t * 8 + 4 * fq); }
;                 bf16_t* rowp = base + (size_t)row * ldc + col0;
; #pragma unroll
;                 for (int bj = 0; bj < 2; ++bj) {
;                     f32x4 v0 = acc[ai][bj][m][0] * rsv, v1 = acc[ai][bj][m][1] * rsv;
;                     if (dorope) {
;                         const f32x4 a0 = v0, a1 = v1;
;                         v0[0] = a0[0] * cs[0] - a0[1] * sn[0]; v0[1] = a0[1] * cs[0] + a0[0] * sn[0];
;                         v0[2] = a0[2] * cs[1] - a0[3] * sn[1]; v0[3] = a0[3] * cs[1] + a0[2] * sn[1];
;                         v1[0] = a1[0] * cs[2] - a1[1] * sn[2]; v1[1] = a1[1] * cs[2] + a1[0] * sn[2];
;                         v1[2] = a1[2] * cs[3] - a1[3] * sn[3]; v1[3] = a1[3] * cs[3] + a1[2] * sn[3];
;                     }
;                     if (dosilu) {
; #pragma unroll
;                         for (int e_ = 0; e_ < 4; ++e_) { v0[e_] = v0[e_] * __builtin_amdgcn_rcpf(1.f + __builtin_amdgcn_exp2f(v0[e_] * -1.4426950408889634f)); v1[e_] = v1[e_] * __builtin_amdgcn_rcpf(1.f + __builtin_amdgcn_exp2f(v1[e_] * -1.4426950408889634f)); }
;                     }
;                     u32x4 w; w.x = cvt_pk_bf16(v0[0], v0[1]); w.y = cvt_pk_bf16(v0[2], v0[3]); w.z = cvt_pk_bf16(v1[0], v1[1]); w.w = cvt_pk_bf16(v1[2], v1[3]);
;                     *(u32x4*)(rowp + bj * HALF) = w;
.LBB0_257:
	v_or_b32_e32 v120, 16, v158
	v_ashrrev_i32_e32 v121, 31, v120
	v_cvt_pk_bf16_f32 v116, v116, v117
	v_cvt_pk_bf16_f32 v117, v118, v119
	v_cvt_pk_bf16_f32 v118, v112, v113
	v_cvt_pk_bf16_f32 v119, v114, v115
	global_store_dwordx4 v[166:167], v[116:119], off offset:256
	v_lshl_add_u64 v[112:113], v[120:121], 2, s[6:7]
	v_mov_b32_e32 v122, v231
	v_mov_b32_e32 v116, 0
	v_mov_b32_e32 v112, 1.0
	v_mov_b32_e32 v113, 1.0
	v_mov_b32_e32 v114, 1.0
	v_mov_b32_e32 v115, 1.0
	v_mov_b32_e32 v117, 0
	v_mov_b32_e32 v118, 0
	v_mov_b32_e32 v119, 0
	s_and_saveexec_b64 s[90:91], s[88:89]
	s_cbranch_execz .LBB0_259
	v_lshlrev_b32_e32 v112, 5, v120
	v_and_b32_e32 v144, 0x3fbe0, v112
	v_lshl_add_u64 v[116:117], v[148:149], 0, v[144:145]
	v_lshl_add_u64 v[112:113], v[146:147], 0, v[144:145]
	global_load_dwordx4 v[112:115], v[112:113], off
	s_nop 0
	global_load_dwordx4 v[116:119], v[116:117], off
	s_waitcnt vmcnt(0)
.LBB0_259:
	s_or_b64 exec, exec, s[90:91]
	v_mul_f32_e32 v122, s81, v122
	v_pk_mul_f32 v[110:111], v[110:111], v[122:123] op_sel_hi:[1,0]
	v_pk_mul_f32 v[108:109], v[108:109], v[122:123] op_sel_hi:[1,0]
	v_pk_mul_f32 v[106:107], v[106:107], v[122:123] op_sel_hi:[1,0]
	s_and_b64 vcc, exec, s[2:3]
	v_pk_mul_f32 v[104:105], v[104:105], v[122:123] op_sel_hi:[1,0]
	s_cbranch_vccnz .LBB0_261
	v_pk_mul_f32 v[126:127], v[108:109], v[116:117] op_sel:[1,0] op_sel_hi:[0,0]
	v_pk_fma_f32 v[124:125], v[108:109], v[112:113], v[126:127] op_sel_hi:[1,0,1] neg_lo:[0,0,1] neg_hi:[0,0,1]
	v_pk_fma_f32 v[108:109], v[108:109], v[112:113], v[126:127] op_sel_hi:[1,0,1]
	v_mov_b32_e32 v126, v113
	v_mov_b32_e32 v127, v117
	v_mul_f32_e32 v108, v111, v117
	v_pk_fma_f32 v[126:127], v[110:111], v[126:127], v[108:109] op_sel_hi:[1,1,0] neg_lo:[0,0,1] neg_hi:[0,0,1]
	v_mov_b32_e32 v128, v117
	v_mov_b32_e32 v129, v113
	v_mul_f32_e32 v108, v111, v113
	v_pk_fma_f32 v[110:111], v[110:111], v[128:129], v[108:109] op_sel_hi:[1,1,0]
	v_mov_b32_e32 v125, v109
	v_pk_mul_f32 v[108:109], v[104:105], v[118:119] op_sel:[1,0] op_sel_hi:[0,0]
	v_pk_fma_f32 v[128:129], v[104:105], v[114:115], v[108:109] op_sel_hi:[1,0,1] neg_lo:[0,0,1] neg_hi:[0,0,1]
	v_pk_fma_f32 v[104:105], v[104:105], v[114:115], v[108:109] op_sel_hi:[1,0,1]
	v_mov_b32_e32 v108, v115
	v_mov_b32_e32 v109, v119
	v_mul_f32_e32 v104, v107, v119
	v_pk_fma_f32 v[130:131], v[106:107], v[108:109], v[104:105] op_sel_hi:[1,1,0] neg_lo:[0,0,1] neg_hi:[0,0,1]
	v_mov_b32_e32 v108, v119
	v_mov_b32_e32 v109, v115
	v_mul_f32_e32 v104, v107, v115
	v_pk_fma_f32 v[106:107], v[106:107], v[108:109], v[104:105] op_sel_hi:[1,1,0]
	v_mov_b32_e32 v129, v105
	v_mov_b32_e32 v127, v110
	v_mov_b32_e32 v131, v106
	v_mov_b64_e32 v[108:109], v[124:125]
	v_mov_b64_e32 v[104:105], v[128:129]
	v_mov_b64_e32 v[110:111], v[126:127]
	v_mov_b64_e32 v[106:107], v[130:131]

; __device__ __forceinline__ unsigned cvt_pk_bf16(float lo, float hi) { unsigned r; asm volatile("v_cvt_pk_bf16_f32 %0, %1, %2" : "=v"(r) : "v"(lo), "v"(hi)); return r; }
;     __device__ __forceinline__ void operator()(const f32x4 (&acc)[2][2][4][2], const Unit& u, int wr, int wc, int fr, int fq) const {
;     ...
;                 const int row = row0 + ai * HALF + m * 16; const float rsv = rs[row] * sc;
;                 f32x4 cs = (f32x4){1.f, 1.f, 1.f, 1.f}, sn = (f32x4){0.f, 0.f, 0.f, 0.f};
;                 if (ropel) { const int t = row & 8191; cs = *(const f32x4*)(rope + t * 8 + 4 * fq); sn = *(const f32x4*)(rope + 65536 + t * 8 + 4 * fq); }
;                 bf16_t* rowp = base + (size_t)row * ldc + col0;
; #pragma unroll
;                 for (int bj = 0; bj < 2; ++bj) {
;                     f32x4 v0 = acc[ai][bj][m][0] * rsv, v1 = acc[ai][bj][m][1] * rsv;
;                     if (dorope) {
;                         const f32x4 a0 = v0, a1 = v1;
;                         v0[0] = a0[0] * cs[0] - a0[1] * sn[0]; v0[1] = a0[1] * cs[0] + a0[0] * sn[0];
;                         v0[2] = a0[2] * cs[1] - a0[3] * sn[1]; v0[3] = a0[3] * cs[1] + a0[2] * sn[1];
;                         v1[0] = a1[0] * cs[2] - a1[1] * sn[2]; v1[1] = a1[1] * cs[2] + a1[0] * sn[2];
;                         v1[2] = a1[2] * cs[3] - a1[3] * sn[3]; v1[3] = a1[3] * cs[3] + a1[2] * sn[3];
;                     }
;                     if (dosilu) {
; #pragma unroll
;                         for (int e_ = 0; e_ < 4; ++e_) { v0[e_] = v0[e_] * __builtin_amdgcn_rcpf(1.f + __builtin_amdgcn_exp2f(v0[e_] * -1.4426950408889634f)); v1[e_] = v1[e_] * __builtin_amdgcn_rcpf(1.f + __builtin_amdgcn_exp2f(v1[e_] * -1.4426950408889634f)); }
;                     }
;                     u32x4 w; w.x = cvt_pk_bf16(v0[0], v0[1]); w.y = cvt_pk_bf16(v0[2], v0[3]); w.z = cvt_pk_bf16(v1[0], v1[1]); w.w = cvt_pk_bf16(v1[2], v1[3]);
;                     *(u32x4*)(rowp + bj * HALF) = w;
.LBB0_267:
	v_or_b32_e32 v104, 32, v158
	v_ashrrev_i32_e32 v105, 31, v104
	v_cvt_pk_bf16_f32 v100, v100, v101
	v_cvt_pk_bf16_f32 v101, v102, v103
	v_cvt_pk_bf16_f32 v102, v96, v97
	v_cvt_pk_bf16_f32 v103, v98, v99
	global_store_dwordx4 v[120:121], v[100:103], off offset:256
	v_lshl_add_u64 v[96:97], v[104:105], 2, s[6:7]
	v_mov_b32_e32 v106, v232
	v_mov_b32_e32 v100, 0
	v_mov_b32_e32 v96, 1.0
	v_mov_b32_e32 v97, 1.0
	v_mov_b32_e32 v98, 1.0
	v_mov_b32_e32 v99, 1.0
	v_mov_b32_e32 v101, 0
	v_mov_b32_e32 v102, 0
	v_mov_b32_e32 v103, 0
	s_and_saveexec_b64 s[90:91], s[88:89]
	s_cbranch_execz .LBB0_269
	v_lshlrev_b32_e32 v96, 5, v104
	v_and_b32_e32 v144, 0x3fde0, v96
	v_lshl_add_u64 v[100:101], v[148:149], 0, v[144:145]
	v_lshl_add_u64 v[96:97], v[146:147], 0, v[144:145]
	global_load_dwordx4 v[96:99], v[96:97], off
	s_nop 0
	global_load_dwordx4 v[100:103], v[100:101], off
	s_waitcnt vmcnt(0)
.LBB0_269:
	s_or_b64 exec, exec, s[90:91]
	v_mul_f32_e32 v106, s81, v106
	v_pk_mul_f32 v[94:95], v[94:95], v[106:107] op_sel_hi:[1,0]
	v_pk_mul_f32 v[92:93], v[92:93], v[106:107] op_sel_hi:[1,0]
	v_pk_mul_f32 v[90:91], v[90:91], v[106:107] op_sel_hi:[1,0]
	s_and_b64 vcc, exec, s[2:3]
	v_pk_mul_f32 v[88:89], v[88:89], v[106:107] op_sel_hi:[1,0]
	s_cbranch_vccnz .LBB0_271
	v_pk_mul_f32 v[110:111], v[92:93], v[100:101] op_sel:[1,0] op_sel_hi:[0,0]
	v_pk_fma_f32 v[108:109], v[92:93], v[96:97], v[110:111] op_sel_hi:[1,0,1] neg_lo:[0,0,1] neg_hi:[0,0,1]
	v_pk_fma_f32 v[92:93], v[92:93], v[96:97], v[110:111] op_sel_hi:[1,0,1]
	v_mov_b32_e32 v110, v97
	v_mov_b32_e32 v111, v101
	v_mul_f32_e32 v92, v95, v101
	v_pk_fma_f32 v[110:111], v[94:95], v[110:111], v[92:93] op_sel_hi:[1,1,0] neg_lo:[0,0,1] neg_hi:[0,0,1]
	v_mov_b32_e32 v112, v101
	v_mov_b32_e32 v113, v97
	v_mul_f32_e32 v92, v95, v97
	v_pk_fma_f32 v[94:95], v[94:95], v[112:113], v[92:93] op_sel_hi:[1,1,0]
	v_mov_b32_e32 v109, v93
	v_pk_mul_f32 v[92:93], v[88:89], v[102:103] op_sel:[1,0] op_sel_hi:[0,0]
	v_pk_fma_f32 v[112:113], v[88:89], v[98:99], v[92:93] op_sel_hi:[1,0,1] neg_lo:[0,0,1] neg_hi:[0,0,1]
	v_pk_fma_f32 v[88:89], v[88:89], v[98:99], v[92:93] op_sel_hi:[1,0,1]
	v_mov_b32_e32 v92, v99
	v_mov_b32_e32 v93, v103
	v_mul_f32_e32 v88, v91, v103
	v_pk_fma_f32 v[114:115], v[90:91], v[92:93], v[88:89] op_sel_hi:[1,1,0] neg_lo:[0,0,1] neg_hi:[0,0,1]
	v_mov_b32_e32 v92, v103
	v_mov_b32_e32 v93, v99
	v_mul_f32_e32 v88, v91, v99
	v_pk_fma_f32 v[90:91], v[90:91], v[92:93], v[88:89] op_sel_hi:[1,1,0]
	v_mov_b32_e32 v113, v89
	v_mov_b32_e32 v111, v94
	v_mov_b32_e32 v115, v90
	v_mov_b64_e32 v[92:93], v[108:109]
	v_mov_b64_e32 v[88:89], v[112:113]
	v_mov_b64_e32 v[94:95], v[110:111]
	v_mov_b64_e32 v[90:91], v[114:115]

; __device__ __forceinline__ unsigned cvt_pk_bf16(float lo, float hi) { unsigned r; asm volatile("v_cvt_pk_bf16_f32 %0, %1, %2" : "=v"(r) : "v"(lo), "v"(hi)); return r; }
;     __device__ __forceinline__ void operator()(const f32x4 (&acc)[2][2][4][2], const Unit& u, int wr, int wc, int fr, int fq) const {
;     ...
;                 const int row = row0 + ai * HALF + m * 16; const float rsv = rs[row] * sc;
;                 f32x4 cs = (f32x4){1.f, 1.f, 1.f, 1.f}, sn = (f32x4){0.f, 0.f, 0.f, 0.f};
;                 if (ropel) { const int t = row & 8191; cs = *(const f32x4*)(rope + t * 8 + 4 * fq); sn = *(const f32x4*)(rope + 65536 + t * 8 + 4 * fq); }
;                 bf16_t* rowp = base + (size_t)row * ldc + col0;
; #pragma unroll
;                 for (int bj = 0; bj < 2; ++bj) {
;                     f32x4 v0 = acc[ai][bj][m][0] * rsv, v1 = acc[ai][bj][m][1] * rsv;
;                     if (dorope) {
;                         const f32x4 a0 = v0, a1 = v1;
;                         v0[0] = a0[0] * cs[0] - a0[1] * sn[0]; v0[1] = a0[1] * cs[0] + a0[0] * sn[0];
;                         v0[2] = a0[2] * cs[1] - a0[3] * sn[1]; v0[3] = a0[3] * cs[1] + a0[2] * sn[1];
;                         v1[0] = a1[0] * cs[2] - a1[1] * sn[2]; v1[1] = a1[1] * cs[2] + a1[0] * sn[2];
;                         v1[2] = a1[2] * cs[3] - a1[3] * sn[3]; v1[3] = a1[3] * cs[3] + a1[2] * sn[3];
;                     }
;                     if (dosilu) {
; #pragma unroll
;                         for (int e_ = 0; e_ < 4; ++e_) { v0[e_] = v0[e_] * __builtin_amdgcn_rcpf(1.f + __builtin_amdgcn_exp2f(v0[e_] * -1.4426950408889634f)); v1[e_] = v1[e_] * __builtin_amdgcn_rcpf(1.f + __builtin_amdgcn_exp2f(v1[e_] * -1.4426950408889634f)); }
;                     }
;                     u32x4 w; w.x = cvt_pk_bf16(v0[0], v0[1]); w.y = cvt_pk_bf16(v0[2], v0[3]); w.z = cvt_pk_bf16(v1[0], v1[1]); w.w = cvt_pk_bf16(v1[2], v1[3]);
;                     *(u32x4*)(rowp + bj * HALF) = w;
.LBB0_277:
	v_or_b32_e32 v88, 48, v158
	v_ashrrev_i32_e32 v89, 31, v88
	v_cvt_pk_bf16_f32 v84, v84, v85
	v_cvt_pk_bf16_f32 v85, v86, v87
	v_cvt_pk_bf16_f32 v86, v80, v81
	v_cvt_pk_bf16_f32 v87, v82, v83
	global_store_dwordx4 v[104:105], v[84:87], off offset:256
	v_lshl_add_u64 v[80:81], v[88:89], 2, s[6:7]
	v_mov_b32_e32 v90, v233
	v_mov_b32_e32 v84, 0
	v_mov_b32_e32 v80, 1.0
	v_mov_b32_e32 v81, 1.0
	v_mov_b32_e32 v82, 1.0
	v_mov_b32_e32 v83, 1.0
	v_mov_b32_e32 v85, 0
	v_mov_b32_e32 v86, 0
	v_mov_b32_e32 v87, 0
	s_and_saveexec_b64 s[90:91], s[88:89]
	s_cbranch_execz .LBB0_279
	v_lshlrev_b32_e32 v80, 5, v88
	v_and_b32_e32 v144, 0x3ffe0, v80
	v_lshl_add_u64 v[84:85], v[148:149], 0, v[144:145]
	v_lshl_add_u64 v[80:81], v[146:147], 0, v[144:145]
	global_load_dwordx4 v[80:83], v[80:81], off
	s_nop 0
	global_load_dwordx4 v[84:87], v[84:85], off
	s_waitcnt vmcnt(0)
.LBB0_279:
	s_or_b64 exec, exec, s[90:91]
	v_mul_f32_e32 v90, s81, v90
	v_pk_mul_f32 v[78:79], v[78:79], v[90:91] op_sel_hi:[1,0]
	v_pk_mul_f32 v[76:77], v[76:77], v[90:91] op_sel_hi:[1,0]
	v_pk_mul_f32 v[74:75], v[74:75], v[90:91] op_sel_hi:[1,0]
	s_and_b64 vcc, exec, s[2:3]
	v_pk_mul_f32 v[72:73], v[72:73], v[90:91] op_sel_hi:[1,0]
	s_cbranch_vccnz .LBB0_281
	v_pk_mul_f32 v[94:95], v[76:77], v[84:85] op_sel:[1,0] op_sel_hi:[0,0]
	v_pk_fma_f32 v[92:93], v[76:77], v[80:81], v[94:95] op_sel_hi:[1,0,1] neg_lo:[0,0,1] neg_hi:[0,0,1]
	v_pk_fma_f32 v[76:77], v[76:77], v[80:81], v[94:95] op_sel_hi:[1,0,1]
	v_mov_b32_e32 v94, v81
	v_mov_b32_e32 v95, v85
	v_mul_f32_e32 v76, v79, v85
	v_pk_fma_f32 v[94:95], v[78:79], v[94:95], v[76:77] op_sel_hi:[1,1,0] neg_lo:[0,0,1] neg_hi:[0,0,1]
	v_mov_b32_e32 v96, v85
	v_mov_b32_e32 v97, v81
	v_mul_f32_e32 v76, v79, v81
	v_pk_fma_f32 v[78:79], v[78:79], v[96:97], v[76:77] op_sel_hi:[1,1,0]
	v_mov_b32_e32 v93, v77
	v_pk_mul_f32 v[76:77], v[72:73], v[86:87] op_sel:[1,0] op_sel_hi:[0,0]
	v_pk_fma_f32 v[96:97], v[72:73], v[82:83], v[76:77] op_sel_hi:[1,0,1] neg_lo:[0,0,1] neg_hi:[0,0,1]
	v_pk_fma_f32 v[72:73], v[72:73], v[82:83], v[76:77] op_sel_hi:[1,0,1]
	v_mov_b32_e32 v76, v83
	v_mov_b32_e32 v77, v87
	v_mul_f32_e32 v72, v75, v87
	v_pk_fma_f32 v[98:99], v[74:75], v[76:77], v[72:73] op_sel_hi:[1,1,0] neg_lo:[0,0,1] neg_hi:[0,0,1]
	v_mov_b32_e32 v76, v87
	v_mov_b32_e32 v77, v83
	v_mul_f32_e32 v72, v75, v83
	v_pk_fma_f32 v[74:75], v[74:75], v[76:77], v[72:73] op_sel_hi:[1,1,0]
	v_mov_b32_e32 v97, v73
	v_mov_b32_e32 v95, v78
	v_mov_b32_e32 v99, v74
	v_mov_b64_e32 v[76:77], v[92:93]
	v_mov_b64_e32 v[72:73], v[96:97]
	v_mov_b64_e32 v[78:79], v[94:95]
	v_mov_b64_e32 v[74:75], v[98:99]

; __device__ __forceinline__ unsigned cvt_pk_bf16(float lo, float hi) { unsigned r; asm volatile("v_cvt_pk_bf16_f32 %0, %1, %2" : "=v"(r) : "v"(lo), "v"(hi)); return r; }
;     __device__ __forceinline__ void operator()(const f32x4 (&acc)[2][2][4][2], const Unit& u, int wr, int wc, int fr, int fq) const {
;     ...
;                 const int row = row0 + ai * HALF + m * 16; const float rsv = rs[row] * sc;
;                 f32x4 cs = (f32x4){1.f, 1.f, 1.f, 1.f}, sn = (f32x4){0.f, 0.f, 0.f, 0.f};
;                 if (ropel) { const int t = row & 8191; cs = *(const f32x4*)(rope + t * 8 + 4 * fq); sn = *(const f32x4*)(rope + 65536 + t * 8 + 4 * fq); }
;                 bf16_t* rowp = base + (size_t)row * ldc + col0;
; #pragma unroll
;                 for (int bj = 0; bj < 2; ++bj) {
;                     f32x4 v0 = acc[ai][bj][m][0] * rsv, v1 = acc[ai][bj][m][1] * rsv;
;                     if (dorope) {
;                         const f32x4 a0 = v0, a1 = v1;
;                         v0[0] = a0[0] * cs[0] - a0[1] * sn[0]; v0[1] = a0[1] * cs[0] + a0[0] * sn[0];
;                         v0[2] = a0[2] * cs[1] - a0[3] * sn[1]; v0[3] = a0[3] * cs[1] + a0[2] * sn[1];
;                         v1[0] = a1[0] * cs[2] - a1[1] * sn[2]; v1[1] = a1[1] * cs[2] + a1[0] * sn[2];
;                         v1[2] = a1[2] * cs[3] - a1[3] * sn[3]; v1[3] = a1[3] * cs[3] + a1[2] * sn[3];
;                     }
;                     if (dosilu) {
; #pragma unroll
;                         for (int e_ = 0; e_ < 4; ++e_) { v0[e_] = v0[e_] * __builtin_amdgcn_rcpf(1.f + __builtin_amdgcn_exp2f(v0[e_] * -1.4426950408889634f)); v1[e_] = v1[e_] * __builtin_amdgcn_rcpf(1.f + __builtin_amdgcn_exp2f(v1[e_] * -1.4426950408889634f)); }
;                     }
;                     u32x4 w; w.x = cvt_pk_bf16(v0[0], v0[1]); w.y = cvt_pk_bf16(v0[2], v0[3]); w.z = cvt_pk_bf16(v1[0], v1[1]); w.w = cvt_pk_bf16(v1[2], v1[3]);
;                     *(u32x4*)(rowp + bj * HALF) = w;
.LBB0_287:
	v_cvt_pk_bf16_f32 v68, v68, v69
	v_cvt_pk_bf16_f32 v69, v70, v71
	v_cvt_pk_bf16_f32 v70, v64, v65
	s_nop 0
	v_cvt_pk_bf16_f32 v71, v66, v67
	global_store_dwordx4 v[88:89], v[68:71], off offset:256
	v_mov_b32_e32 v72, v234
	v_add_u32_e32 v74, 0x80, v158
	v_ashrrev_i32_e32 v75, 31, v74
	v_mov_b32_e32 v68, 0
	v_mov_b32_e32 v64, 1.0
	v_mov_b32_e32 v65, 1.0
	v_mov_b32_e32 v66, 1.0
	v_mov_b32_e32 v67, 1.0
	v_mov_b32_e32 v69, 0
	v_mov_b32_e32 v70, 0
	v_mov_b32_e32 v71, 0
	s_and_saveexec_b64 s[90:91], s[88:89]
	s_cbranch_execz .LBB0_289
	v_lshlrev_b32_e32 v64, 5, v74
	v_and_b32_e32 v144, 0x3f9e0, v64
	v_lshl_add_u64 v[68:69], v[148:149], 0, v[144:145]
	v_lshl_add_u64 v[64:65], v[146:147], 0, v[144:145]
	global_load_dwordx4 v[64:67], v[64:65], off
	s_nop 0
	global_load_dwordx4 v[68:71], v[68:69], off
	s_waitcnt vmcnt(0)
.LBB0_289:
	s_or_b64 exec, exec, s[90:91]
	v_mul_f32_e32 v72, s81, v72
	v_pk_mul_f32 v[62:63], v[62:63], v[72:73] op_sel_hi:[1,0]
	v_pk_mul_f32 v[60:61], v[60:61], v[72:73] op_sel_hi:[1,0]
	v_pk_mul_f32 v[58:59], v[58:59], v[72:73] op_sel_hi:[1,0]
	s_and_b64 vcc, exec, s[2:3]
	v_pk_mul_f32 v[56:57], v[56:57], v[72:73] op_sel_hi:[1,0]
	s_cbranch_vccnz .LBB0_291
	v_pk_mul_f32 v[78:79], v[60:61], v[68:69] op_sel:[1,0] op_sel_hi:[0,0]
	v_pk_fma_f32 v[76:77], v[60:61], v[64:65], v[78:79] op_sel_hi:[1,0,1] neg_lo:[0,0,1] neg_hi:[0,0,1]
	v_pk_fma_f32 v[60:61], v[60:61], v[64:65], v[78:79] op_sel_hi:[1,0,1]
	v_mov_b32_e32 v78, v65
	v_mov_b32_e32 v79, v69
	v_mul_f32_e32 v60, v63, v69
	v_pk_fma_f32 v[78:79], v[62:63], v[78:79], v[60:61] op_sel_hi:[1,1,0] neg_lo:[0,0,1] neg_hi:[0,0,1]
	v_mov_b32_e32 v80, v69
	v_mov_b32_e32 v81, v65
	v_mul_f32_e32 v60, v63, v65
	v_pk_fma_f32 v[62:63], v[62:63], v[80:81], v[60:61] op_sel_hi:[1,1,0]
	v_mov_b32_e32 v77, v61
	v_pk_mul_f32 v[60:61], v[56:57], v[70:71] op_sel:[1,0] op_sel_hi:[0,0]
	v_pk_fma_f32 v[80:81], v[56:57], v[66:67], v[60:61] op_sel_hi:[1,0,1] neg_lo:[0,0,1] neg_hi:[0,0,1]
	v_pk_fma_f32 v[56:57], v[56:57], v[66:67], v[60:61] op_sel_hi:[1,0,1]
	v_mov_b32_e32 v60, v67
	v_mov_b32_e32 v61, v71
	v_mul_f32_e32 v56, v59, v71
	v_pk_fma_f32 v[82:83], v[58:59], v[60:61], v[56:57] op_sel_hi:[1,1,0] neg_lo:[0,0,1] neg_hi:[0,0,1]
	v_mov_b32_e32 v60, v71
	v_mov_b32_e32 v61, v67
	v_mul_f32_e32 v56, v59, v67
	v_pk_fma_f32 v[58:59], v[58:59], v[60:61], v[56:57] op_sel_hi:[1,1,0]
	v_mov_b32_e32 v81, v57
	v_mov_b32_e32 v79, v62
	v_mov_b32_e32 v83, v58
	v_mov_b64_e32 v[60:61], v[76:77]
	v_mov_b64_e32 v[56:57], v[80:81]
	v_mov_b64_e32 v[62:63], v[78:79]
	v_mov_b64_e32 v[58:59], v[82:83]

; __device__ __forceinline__ unsigned cvt_pk_bf16(float lo, float hi) { unsigned r; asm volatile("v_cvt_pk_bf16_f32 %0, %1, %2" : "=v"(r) : "v"(lo), "v"(hi)); return r; }
;     __device__ __forceinline__ void operator()(const f32x4 (&acc)[2][2][4][2], const Unit& u, int wr, int wc, int fr, int fq) const {
;     ...
;                 const int row = row0 + ai * HALF + m * 16; const float rsv = rs[row] * sc;
;                 f32x4 cs = (f32x4){1.f, 1.f, 1.f, 1.f}, sn = (f32x4){0.f, 0.f, 0.f, 0.f};
;                 if (ropel) { const int t = row & 8191; cs = *(const f32x4*)(rope + t * 8 + 4 * fq); sn = *(const f32x4*)(rope + 65536 + t * 8 + 4 * fq); }
;                 bf16_t* rowp = base + (size_t)row * ldc + col0;
; #pragma unroll
;                 for (int bj = 0; bj < 2; ++bj) {
;                     f32x4 v0 = acc[ai][bj][m][0] * rsv, v1 = acc[ai][bj][m][1] * rsv;
;                     if (dorope) {
;                         const f32x4 a0 = v0, a1 = v1;
;                         v0[0] = a0[0] * cs[0] - a0[1] * sn[0]; v0[1] = a0[1] * cs[0] + a0[0] * sn[0];
;                         v0[2] = a0[2] * cs[1] - a0[3] * sn[1]; v0[3] = a0[3] * cs[1] + a0[2] * sn[1];
;                         v1[0] = a1[0] * cs[2] - a1[1] * sn[2]; v1[1] = a1[1] * cs[2] + a1[0] * sn[2];
;                         v1[2] = a1[2] * cs[3] - a1[3] * sn[3]; v1[3] = a1[3] * cs[3] + a1[2] * sn[3];
;                     }
;                     if (dosilu) {
; #pragma unroll
;                         for (int e_ = 0; e_ < 4; ++e_) { v0[e_] = v0[e_] * __builtin_amdgcn_rcpf(1.f + __builtin_amdgcn_exp2f(v0[e_] * -1.4426950408889634f)); v1[e_] = v1[e_] * __builtin_amdgcn_rcpf(1.f + __builtin_amdgcn_exp2f(v1[e_] * -1.4426950408889634f)); }
;                     }
;                     u32x4 w; w.x = cvt_pk_bf16(v0[0], v0[1]); w.y = cvt_pk_bf16(v0[2], v0[3]); w.z = cvt_pk_bf16(v1[0], v1[1]); w.w = cvt_pk_bf16(v1[2], v1[3]);
;                     *(u32x4*)(rowp + bj * HALF) = w;
.LBB0_297:
	v_cvt_pk_bf16_f32 v52, v52, v53
	v_cvt_pk_bf16_f32 v53, v54, v55
	v_cvt_pk_bf16_f32 v54, v48, v49
	s_nop 0
	v_cvt_pk_bf16_f32 v55, v50, v51
	global_store_dwordx4 v[74:75], v[52:55], off offset:256
	v_mov_b32_e32 v56, v235
	v_add_u32_e32 v58, 0x90, v158
	v_ashrrev_i32_e32 v59, 31, v58
	v_mov_b32_e32 v52, 0
	v_mov_b32_e32 v48, 1.0
	v_mov_b32_e32 v49, 1.0
	v_mov_b32_e32 v50, 1.0
	v_mov_b32_e32 v51, 1.0
	v_mov_b32_e32 v53, 0
	v_mov_b32_e32 v54, 0
	v_mov_b32_e32 v55, 0
	s_and_saveexec_b64 s[90:91], s[88:89]
	s_cbranch_execz .LBB0_299
	v_lshlrev_b32_e32 v48, 5, v58
	v_and_b32_e32 v144, 0x3fbe0, v48
	v_lshl_add_u64 v[52:53], v[148:149], 0, v[144:145]
	v_lshl_add_u64 v[48:49], v[146:147], 0, v[144:145]
	global_load_dwordx4 v[48:51], v[48:49], off
	s_nop 0
	global_load_dwordx4 v[52:55], v[52:53], off
	s_waitcnt vmcnt(0)
.LBB0_299:
	s_or_b64 exec, exec, s[90:91]
	v_mul_f32_e32 v56, s81, v56
	v_pk_mul_f32 v[46:47], v[46:47], v[56:57] op_sel_hi:[1,0]
	v_pk_mul_f32 v[44:45], v[44:45], v[56:57] op_sel_hi:[1,0]
	v_pk_mul_f32 v[42:43], v[42:43], v[56:57] op_sel_hi:[1,0]
	s_and_b64 vcc, exec, s[2:3]
	v_pk_mul_f32 v[40:41], v[40:41], v[56:57] op_sel_hi:[1,0]
	s_cbranch_vccnz .LBB0_301
	v_pk_mul_f32 v[62:63], v[44:45], v[52:53] op_sel:[1,0] op_sel_hi:[0,0]
	v_pk_fma_f32 v[60:61], v[44:45], v[48:49], v[62:63] op_sel_hi:[1,0,1] neg_lo:[0,0,1] neg_hi:[0,0,1]
	v_pk_fma_f32 v[44:45], v[44:45], v[48:49], v[62:63] op_sel_hi:[1,0,1]
	v_mov_b32_e32 v62, v49
	v_mov_b32_e32 v63, v53
	v_mul_f32_e32 v44, v47, v53
	v_pk_fma_f32 v[62:63], v[46:47], v[62:63], v[44:45] op_sel_hi:[1,1,0] neg_lo:[0,0,1] neg_hi:[0,0,1]
	v_mov_b32_e32 v64, v53
	v_mov_b32_e32 v65, v49
	v_mul_f32_e32 v44, v47, v49
	v_pk_fma_f32 v[46:47], v[46:47], v[64:65], v[44:45] op_sel_hi:[1,1,0]
	v_mov_b32_e32 v61, v45
	v_pk_mul_f32 v[44:45], v[40:41], v[54:55] op_sel:[1,0] op_sel_hi:[0,0]
	v_pk_fma_f32 v[64:65], v[40:41], v[50:51], v[44:45] op_sel_hi:[1,0,1] neg_lo:[0,0,1] neg_hi:[0,0,1]
	v_pk_fma_f32 v[40:41], v[40:41], v[50:51], v[44:45] op_sel_hi:[1,0,1]
	v_mov_b32_e32 v44, v51
	v_mov_b32_e32 v45, v55
	v_mul_f32_e32 v40, v43, v55
	v_pk_fma_f32 v[66:67], v[42:43], v[44:45], v[40:41] op_sel_hi:[1,1,0] neg_lo:[0,0,1] neg_hi:[0,0,1]
	v_mov_b32_e32 v44, v55
	v_mov_b32_e32 v45, v51
	v_mul_f32_e32 v40, v43, v51
	v_pk_fma_f32 v[42:43], v[42:43], v[44:45], v[40:41] op_sel_hi:[1,1,0]
	v_mov_b32_e32 v65, v41
	v_mov_b32_e32 v63, v46
	v_mov_b32_e32 v67, v42
	v_mov_b64_e32 v[44:45], v[60:61]
	v_mov_b64_e32 v[40:41], v[64:65]
	v_mov_b64_e32 v[46:47], v[62:63]
	v_mov_b64_e32 v[42:43], v[66:67]

; __device__ __forceinline__ unsigned cvt_pk_bf16(float lo, float hi) { unsigned r; asm volatile("v_cvt_pk_bf16_f32 %0, %1, %2" : "=v"(r) : "v"(lo), "v"(hi)); return r; }
;     __device__ __forceinline__ void operator()(const f32x4 (&acc)[2][2][4][2], const Unit& u, int wr, int wc, int fr, int fq) const {
;     ...
;                 const int row = row0 + ai * HALF + m * 16; const float rsv = rs[row] * sc;
;                 f32x4 cs = (f32x4){1.f, 1.f, 1.f, 1.f}, sn = (f32x4){0.f, 0.f, 0.f, 0.f};
;                 if (ropel) { const int t = row & 8191; cs = *(const f32x4*)(rope + t * 8 + 4 * fq); sn = *(const f32x4*)(rope + 65536 + t * 8 + 4 * fq); }
;                 bf16_t* rowp = base + (size_t)row * ldc + col0;
; #pragma unroll
;                 for (int bj = 0; bj < 2; ++bj) {
;                     f32x4 v0 = acc[ai][bj][m][0] * rsv, v1 = acc[ai][bj][m][1] * rsv;
;                     if (dorope) {
;                         const f32x4 a0 = v0, a1 = v1;
;                         v0[0] = a0[0] * cs[0] - a0[1] * sn[0]; v0[1] = a0[1] * cs[0] + a0[0] * sn[0];
;                         v0[2] = a0[2] * cs[1] - a0[3] * sn[1]; v0[3] = a0[3] * cs[1] + a0[2] * sn[1];
;                         v1[0] = a1[0] * cs[2] - a1[1] * sn[2]; v1[1] = a1[1] * cs[2] + a1[0] * sn[2];
;                         v1[2] = a1[2] * cs[3] - a1[3] * sn[3]; v1[3] = a1[3] * cs[3] + a1[2] * sn[3];
;                     }
;                     if (dosilu) {
; #pragma unroll
;                         for (int e_ = 0; e_ < 4; ++e_) { v0[e_] = v0[e_] * __builtin_amdgcn_rcpf(1.f + __builtin_amdgcn_exp2f(v0[e_] * -1.4426950408889634f)); v1[e_] = v1[e_] * __builtin_amdgcn_rcpf(1.f + __builtin_amdgcn_exp2f(v1[e_] * -1.4426950408889634f)); }
;                     }
;                     u32x4 w; w.x = cvt_pk_bf16(v0[0], v0[1]); w.y = cvt_pk_bf16(v0[2], v0[3]); w.z = cvt_pk_bf16(v1[0], v1[1]); w.w = cvt_pk_bf16(v1[2], v1[3]);
;                     *(u32x4*)(rowp + bj * HALF) = w;
.LBB0_307:
	v_cvt_pk_bf16_f32 v36, v36, v37
	v_cvt_pk_bf16_f32 v37, v38, v39
	v_cvt_pk_bf16_f32 v38, v32, v33
	s_nop 0
	v_cvt_pk_bf16_f32 v39, v34, v35
	global_store_dwordx4 v[58:59], v[36:39], off offset:256
	v_mov_b32_e32 v40, v236
	v_add_u32_e32 v42, 0xa0, v158
	v_ashrrev_i32_e32 v43, 31, v42
	v_mov_b32_e32 v36, 0
	v_mov_b32_e32 v32, 1.0
	v_mov_b32_e32 v33, 1.0
	v_mov_b32_e32 v34, 1.0
	v_mov_b32_e32 v35, 1.0
	v_mov_b32_e32 v37, 0
	v_mov_b32_e32 v38, 0
	v_mov_b32_e32 v39, 0
	s_and_saveexec_b64 s[90:91], s[88:89]
	s_cbranch_execz .LBB0_309
	v_lshlrev_b32_e32 v32, 5, v42
	v_and_b32_e32 v144, 0x3fde0, v32
	v_lshl_add_u64 v[36:37], v[148:149], 0, v[144:145]
	v_lshl_add_u64 v[32:33], v[146:147], 0, v[144:145]
	global_load_dwordx4 v[32:35], v[32:33], off
	s_nop 0
	global_load_dwordx4 v[36:39], v[36:37], off
	s_waitcnt vmcnt(0)
.LBB0_309:
	s_or_b64 exec, exec, s[90:91]
	v_mul_f32_e32 v40, s81, v40
	v_pk_mul_f32 v[30:31], v[30:31], v[40:41] op_sel_hi:[1,0]
	v_pk_mul_f32 v[28:29], v[28:29], v[40:41] op_sel_hi:[1,0]
	v_pk_mul_f32 v[26:27], v[26:27], v[40:41] op_sel_hi:[1,0]
	s_and_b64 vcc, exec, s[2:3]
	v_pk_mul_f32 v[24:25], v[24:25], v[40:41] op_sel_hi:[1,0]
	s_cbranch_vccnz .LBB0_311
	v_pk_mul_f32 v[46:47], v[28:29], v[36:37] op_sel:[1,0] op_sel_hi:[0,0]
	v_pk_fma_f32 v[44:45], v[28:29], v[32:33], v[46:47] op_sel_hi:[1,0,1] neg_lo:[0,0,1] neg_hi:[0,0,1]
	v_pk_fma_f32 v[28:29], v[28:29], v[32:33], v[46:47] op_sel_hi:[1,0,1]
	v_mov_b32_e32 v46, v33
	v_mov_b32_e32 v47, v37
	v_mul_f32_e32 v28, v31, v37
	v_pk_fma_f32 v[46:47], v[30:31], v[46:47], v[28:29] op_sel_hi:[1,1,0] neg_lo:[0,0,1] neg_hi:[0,0,1]
	v_mov_b32_e32 v48, v37
	v_mov_b32_e32 v49, v33
	v_mul_f32_e32 v28, v31, v33
	v_pk_fma_f32 v[30:31], v[30:31], v[48:49], v[28:29] op_sel_hi:[1,1,0]
	v_mov_b32_e32 v45, v29
	v_pk_mul_f32 v[28:29], v[24:25], v[38:39] op_sel:[1,0] op_sel_hi:[0,0]
	v_pk_fma_f32 v[48:49], v[24:25], v[34:35], v[28:29] op_sel_hi:[1,0,1] neg_lo:[0,0,1] neg_hi:[0,0,1]
	v_pk_fma_f32 v[24:25], v[24:25], v[34:35], v[28:29] op_sel_hi:[1,0,1]
	v_mov_b32_e32 v28, v35
	v_mov_b32_e32 v29, v39
	v_mul_f32_e32 v24, v27, v39
	v_pk_fma_f32 v[50:51], v[26:27], v[28:29], v[24:25] op_sel_hi:[1,1,0] neg_lo:[0,0,1] neg_hi:[0,0,1]
	v_mov_b32_e32 v28, v39
	v_mov_b32_e32 v29, v35
	v_mul_f32_e32 v24, v27, v35
	v_pk_fma_f32 v[26:27], v[26:27], v[28:29], v[24:25] op_sel_hi:[1,1,0]
	v_mov_b32_e32 v49, v25
	v_mov_b32_e32 v47, v30
	v_mov_b32_e32 v51, v26
	v_mov_b64_e32 v[28:29], v[44:45]
	v_mov_b64_e32 v[24:25], v[48:49]
	v_mov_b64_e32 v[30:31], v[46:47]
	v_mov_b64_e32 v[26:27], v[50:51]

; __device__ __forceinline__ unsigned cvt_pk_bf16(float lo, float hi) { unsigned r; asm volatile("v_cvt_pk_bf16_f32 %0, %1, %2" : "=v"(r) : "v"(lo), "v"(hi)); return r; }
;     __device__ __forceinline__ void operator()(const f32x4 (&acc)[2][2][4][2], const Unit& u, int wr, int wc, int fr, int fq) const {
;     ...
;                 const int row = row0 + ai * HALF + m * 16; const float rsv = rs[row] * sc;
;                 f32x4 cs = (f32x4){1.f, 1.f, 1.f, 1.f}, sn = (f32x4){0.f, 0.f, 0.f, 0.f};
;                 if (ropel) { const int t = row & 8191; cs = *(const f32x4*)(rope + t * 8 + 4 * fq); sn = *(const f32x4*)(rope + 65536 + t * 8 + 4 * fq); }
;                 bf16_t* rowp = base + (size_t)row * ldc + col0;
; #pragma unroll
;                 for (int bj = 0; bj < 2; ++bj) {
;                     f32x4 v0 = acc[ai][bj][m][0] * rsv, v1 = acc[ai][bj][m][1] * rsv;
;                     if (dorope) {
;                         const f32x4 a0 = v0, a1 = v1;
;                         v0[0] = a0[0] * cs[0] - a0[1] * sn[0]; v0[1] = a0[1] * cs[0] + a0[0] * sn[0];
;                         v0[2] = a0[2] * cs[1] - a0[3] * sn[1]; v0[3] = a0[3] * cs[1] + a0[2] * sn[1];
;                         v1[0] = a1[0] * cs[2] - a1[1] * sn[2]; v1[1] = a1[1] * cs[2] + a1[0] * sn[2];
;                         v1[2] = a1[2] * cs[3] - a1[3] * sn[3]; v1[3] = a1[3] * cs[3] + a1[2] * sn[3];
;                     }
;                     if (dosilu) {
; #pragma unroll
;                         for (int e_ = 0; e_ < 4; ++e_) { v0[e_] = v0[e_] * __builtin_amdgcn_rcpf(1.f + __builtin_amdgcn_exp2f(v0[e_] * -1.4426950408889634f)); v1[e_] = v1[e_] * __builtin_amdgcn_rcpf(1.f + __builtin_amdgcn_exp2f(v1[e_] * -1.4426950408889634f)); }
;                     }
;                     u32x4 w; w.x = cvt_pk_bf16(v0[0], v0[1]); w.y = cvt_pk_bf16(v0[2], v0[3]); w.z = cvt_pk_bf16(v1[0], v1[1]); w.w = cvt_pk_bf16(v1[2], v1[3]);
;                     *(u32x4*)(rowp + bj * HALF) = w;
.LBB0_317:
	v_cvt_pk_bf16_f32 v20, v20, v21
	v_cvt_pk_bf16_f32 v21, v22, v23
	v_cvt_pk_bf16_f32 v22, v16, v17
	s_nop 0
	v_cvt_pk_bf16_f32 v23, v18, v19
	global_store_dwordx4 v[42:43], v[20:23], off offset:256
	v_mov_b32_e32 v24, v237
	v_add_u32_e32 v26, 0xb0, v158
	v_ashrrev_i32_e32 v27, 31, v26
	v_mov_b32_e32 v20, 0
	v_mov_b32_e32 v16, 1.0
	v_mov_b32_e32 v17, 1.0
	v_mov_b32_e32 v18, 1.0
	v_mov_b32_e32 v19, 1.0
	v_mov_b32_e32 v21, 0
	v_mov_b32_e32 v22, 0
	v_mov_b32_e32 v23, 0
	s_and_saveexec_b64 s[90:91], s[88:89]
	s_cbranch_execz .LBB0_319
	v_lshlrev_b32_e32 v16, 5, v26
	v_and_b32_e32 v144, 0x3ffe0, v16
	v_lshl_add_u64 v[20:21], v[148:149], 0, v[144:145]
	v_lshl_add_u64 v[16:17], v[146:147], 0, v[144:145]
	global_load_dwordx4 v[16:19], v[16:17], off
	s_nop 0
	global_load_dwordx4 v[20:23], v[20:21], off
	s_waitcnt vmcnt(0)
.LBB0_319:
	s_or_b64 exec, exec, s[90:91]
	v_mul_f32_e32 v24, s81, v24
	v_pk_mul_f32 v[14:15], v[14:15], v[24:25] op_sel_hi:[1,0]
	v_pk_mul_f32 v[12:13], v[12:13], v[24:25] op_sel_hi:[1,0]
	v_pk_mul_f32 v[10:11], v[10:11], v[24:25] op_sel_hi:[1,0]
	s_and_b64 vcc, exec, s[2:3]
	v_pk_mul_f32 v[8:9], v[8:9], v[24:25] op_sel_hi:[1,0]
	s_cbranch_vccnz .LBB0_321
	v_pk_mul_f32 v[30:31], v[12:13], v[20:21] op_sel:[1,0] op_sel_hi:[0,0]
	v_pk_fma_f32 v[28:29], v[12:13], v[16:17], v[30:31] op_sel_hi:[1,0,1] neg_lo:[0,0,1] neg_hi:[0,0,1]
	v_pk_fma_f32 v[12:13], v[12:13], v[16:17], v[30:31] op_sel_hi:[1,0,1]
	v_mov_b32_e32 v30, v17
	v_mov_b32_e32 v31, v21
	v_mul_f32_e32 v12, v15, v21
	v_pk_fma_f32 v[30:31], v[14:15], v[30:31], v[12:13] op_sel_hi:[1,1,0] neg_lo:[0,0,1] neg_hi:[0,0,1]
	v_mov_b32_e32 v32, v21
	v_mov_b32_e32 v33, v17
	v_mul_f32_e32 v12, v15, v17
	v_pk_fma_f32 v[14:15], v[14:15], v[32:33], v[12:13] op_sel_hi:[1,1,0]
	v_mov_b32_e32 v29, v13
	v_pk_mul_f32 v[12:13], v[8:9], v[22:23] op_sel:[1,0] op_sel_hi:[0,0]
	v_pk_fma_f32 v[32:33], v[8:9], v[18:19], v[12:13] op_sel_hi:[1,0,1] neg_lo:[0,0,1] neg_hi:[0,0,1]
	v_pk_fma_f32 v[8:9], v[8:9], v[18:19], v[12:13] op_sel_hi:[1,0,1]
	v_mov_b32_e32 v12, v19
	v_mov_b32_e32 v13, v23
	v_mul_f32_e32 v8, v11, v23
	v_pk_fma_f32 v[34:35], v[10:11], v[12:13], v[8:9] op_sel_hi:[1,1,0] neg_lo:[0,0,1] neg_hi:[0,0,1]
	v_mov_b32_e32 v12, v23
	v_mov_b32_e32 v13, v19
	v_mul_f32_e32 v8, v11, v19
	v_pk_fma_f32 v[10:11], v[10:11], v[12:13], v[8:9] op_sel_hi:[1,1,0]
	v_mov_b32_e32 v33, v9
	v_mov_b32_e32 v31, v14
	v_mov_b32_e32 v35, v10
	v_mov_b64_e32 v[12:13], v[28:29]
	v_mov_b64_e32 v[8:9], v[32:33]
	v_mov_b64_e32 v[14:15], v[30:31]
	v_mov_b64_e32 v[10:11], v[34:35]
